# phase 4 pass B rebalanced: per XCD chunk block 0 keeps 2 tiles and block 16 takes 3 (flag + L2 writeback/invalidate handoff for the one cross-block tile), 5 tile-pass rounds instead of 6
# speedup vs baseline: 1.0033x; 1.0033x over previous
; #define PG8_LAS __attribute__((address_space(3)))
; __device__ __forceinline__ void tile_range(int N, int& lo, int& hi, int& step) {
;   if ((gridDim.x & 7) == 0) {
;     const int x = blockIdx.x & 7, l = blockIdx.x >> 3;
;     lo = (int)((long long)x * N / 8) + l; hi = (int)((long long)(x + 1) * N / 8); step = gridDim.x >> 3;
;   } else { lo = blockIdx.x; hi = N; step = gridDim.x; }
; }
; __device__ void phase4(const Params& p, unsigned char* smem) {
;     ...
;   {
;     pg8::Gemm g; g.A = (const u16*)(p.ws + OFF_QB); g.Bt = (const u16*)(p.ws + OFF_WOB); g.K = 512;
;     EpiGateB E; E.ws = p.ws;
;     pg8::gemm_phase((PG8_LAS unsigned char*)smem, g, S, E);
.LBB0_699:
	s_andn2_b64 vcc, exec, s[6:7]
	v_readfirstlane_b32 s33, v1
	s_cbranch_vccnz .LBB0_718
	s_cmp_eq_u32 s0, 32
	s_cbranch_scc0 .Lp4r_done
	s_lshr_b32 s8, s94, 3
	s_cmp_eq_u32 s8, 16
	s_cbranch_scc0 .Lp4r_n16
	s_mov_b32 s0, 16
	s_add_i32 s3, s3, -1
	s_branch .Lp4r_done
.Lp4r_n16:
	s_cmp_eq_u32 s8, 0
	s_cbranch_scc0 .Lp4r_done
	s_mov_b32 s0, 64
	v_cmp_eq_u32_e32 vcc, 0, v0
	s_and_saveexec_b64 s[8:9], vcc
	s_cbranch_execz .Lp4r_pub
	buffer_wbl2 sc1
	s_waitcnt vmcnt(0)
	s_and_b32 s10, s94, 7
	s_lshl_b32 s10, s10, 8
	s_add_i32 s10, s10, 0xb23400
	v_mov_b32_e32 v2, s10
	v_mov_b32_e32 v3, 1
	global_atomic_add v2, v3, s[88:89]

; __device__ __forceinline__ void tile_decode(int i, int NF, int& ft, int& tt) {
;   const int full = 128 * NF;
;   if (i < full) { const int g = i / (4 * NF); const int rem = i - g * 4 * NF; ft = rem >> 2; tt = 4 * g + (rem & 3); }
;   else { const int rem = i - full; ft = rem >> 1; tt = 128 + (rem & 1); }
.Lp4r_done:
	s_cmpk_gt_i32 s1, 0x1ff
	s_cbranch_scc0 .LBB0_702
	s_add_i32 s6, s1, 0xfffffe00
	s_lshr_b32 s22, s6, 1
	s_and_b32 s6, s1, 1
	s_or_b32 s24, s6, 0x80
	s_cbranch_execz .LBB0_703
	s_branch .LBB0_704

; #define PG8_STAGE(bufoff, gbase, voff) do { _Pragma("unroll") for (int _i = 0; _i < 2; ++_i) \
;         __builtin_amdgcn_global_load_lds((const unsigned*)((const char*)(gbase) + (voff)[_i]), (PG8_LAS unsigned*)(lds + (bufoff) + ldsw + _i * 8192), 16, 0, 0); } while (0)
; #define PG8_LDA(dst, b, h) do { _Pragma("unroll") for (int m = 0; m < 4; ++m) _Pragma("unroll") for (int k = 0; k < 2; ++k) dst[m][k] = *(const PG8_LAS bf16x8*)(lds + PG8_SA(b, h) + aoff + m * 2048 + k * 1024); } while (0)
; #define PG8_LDB(dst, b, h) do { _Pragma("unroll") for (int n = 0; n < 2; ++n) _Pragma("unroll") for (int k = 0; k < 2; ++k) dst[n][k] = *(const PG8_LAS bf16x8*)(lds + PG8_SB(b, h) + boff + n * 2048 + k * 1024); } while (0)
; #define PG8_MMA(ai, bj, At, Bt) do { __builtin_amdgcn_s_setprio(1); _Pragma("unroll") for (int m = 0; m < 4; ++m) _Pragma("unroll") for (int n = 0; n < 2; ++n) _Pragma("unroll") for (int k = 0; k < 2; ++k) \
;         acc[ai][bj][m][n] = __builtin_amdgcn_mfma_f32_16x16x32_bf16(Bt[n][k], At[m][k], acc[ai][bj][m][n], 0, 0, 0); __builtin_amdgcn_s_setprio(0); } while (0)
; #define PG8_WAIT_V(n) asm volatile("s_waitcnt vmcnt(" #n ")" ::: "memory")
; #define PG8_WAIT_L(n) asm volatile("s_waitcnt lgkmcnt(" #n ")" ::: "memory")
; template <class Epi, class Sched>
; __device__ __forceinline__ void gemm_phase(PG8_LAS unsigned char* lds, const Gemm g, const Sched& S, const Epi& E) {
;     ...
;         for (int t = 0; t < nt; t += 2) {
;             const bool last = (t == nt - 2);
;             const char* a1 = cA + (size_t)(t + 1) * kstep;
;             const char* a2 = last ? nA : cA + (size_t)(t + 2) * kstep; const char* b2 = last ? nB : cB + (size_t)(t + 2) * kstep;
;             const char* a3 = a2 + kstep; const char* b3 = b2 + kstep;
;             PG8_LDB(B0, 0, 0); PG8_SCHED; PG8_LDA(At, 0, 0); PG8_STAGE(PG8_SA(1, 1), a1 + hstep, voffA);
;             PG8_WAIT_L(8); PG8_BAR; PG8_WAIT_L(0); PG8_MMA(0, 0, At, B0); PG8_BAR; PG8_SCHED;
;             PG8_LDB(B1, 0, 1); PG8_STAGE(PG8_SB(0, 0), b2, voffB);
;             PG8_BAR; PG8_WAIT_L(0); PG8_MMA(0, 1, At, B1); PG8_BAR;
;             PG8_LDA(At, 0, 1); PG8_STAGE(PG8_SA(0, 0), a2, voffA);
;             PG8_BAR; PG8_WAIT_L(0); PG8_MMA(1, 0, At, B0); PG8_BAR; PG8_SCHED;
;             PG8_STAGE(PG8_SB(0, 1), b2 + hstep, voffB);
;             PG8_WAIT_V(6); PG8_BAR; PG8_MMA(1, 1, At, B1); PG8_BAR;
.LBB0_713:
	ds_read_b128 v[138:141], v157
	ds_read_b128 v[142:145], v158
	ds_read_b128 v[146:149], v159
	ds_read_b128 v[150:153], v160
	s_add_u32 s28, s26, 0xfffe0080
	s_addc_u32 s29, s27, -1
	s_cmp_eq_u32 s61, 4
	s_cselect_b32 s31, s15, s29
	s_cselect_b32 s30, s57, s28
	s_cselect_b32 s29, s13, s60
	s_cselect_b32 s28, s58, s59
	s_mov_b32 m0, s51
	v_lshl_add_u64 v[206:207], s[26:27], 0, v[134:135]
	ds_read_b128 v[174:177], v155
	ds_read_b128 v[178:181], v155 offset:1024
	ds_read_b128 v[182:185], v155 offset:2048
	ds_read_b128 v[186:189], v155 offset:3072
	ds_read_b128 v[190:193], v155 offset:4096
	ds_read_b128 v[194:197], v155 offset:5120
	ds_read_b128 v[198:201], v155 offset:6144
	ds_read_b128 v[202:205], v155 offset:7168
	global_load_lds_dwordx4 v[206:207], off
	v_lshl_add_u64 v[206:207], s[26:27], 0, v[136:137]
	s_mov_b32 m0, s56
	s_nop 0
	global_load_lds_dwordx4 v[206:207], off
	s_waitcnt lgkmcnt(8)
	s_barrier
	s_waitcnt lgkmcnt(0)
	s_setprio 1
	s_waitcnt lgkmcnt(0)
	v_mfma_f32_16x16x32_bf16 v[126:129], v[138:141], v[174:177], v[126:129]
	v_mfma_f32_16x16x32_bf16 v[122:125], v[146:149], v[174:177], v[122:125]
	v_mfma_f32_16x16x32_bf16 v[110:113], v[138:141], v[182:185], v[110:113]
	v_mfma_f32_16x16x32_bf16 v[106:109], v[146:149], v[182:185], v[106:109]
	v_mfma_f32_16x16x32_bf16 v[98:101], v[138:141], v[190:193], v[98:101]
	v_mfma_f32_16x16x32_bf16 v[90:93], v[146:149], v[190:193], v[90:93]
	v_mfma_f32_16x16x32_bf16 v[86:89], v[138:141], v[198:201], v[86:89]
	v_mfma_f32_16x16x32_bf16 v[82:85], v[146:149], v[198:201], v[82:85]
	v_mfma_f32_16x16x32_bf16 v[126:129], v[142:145], v[178:181], v[126:129]
	v_mfma_f32_16x16x32_bf16 v[122:125], v[150:153], v[178:181], v[122:125]
	v_mfma_f32_16x16x32_bf16 v[110:113], v[142:145], v[186:189], v[110:113]
	v_mfma_f32_16x16x32_bf16 v[106:109], v[150:153], v[186:189], v[106:109]
	v_mfma_f32_16x16x32_bf16 v[98:101], v[142:145], v[194:197], v[98:101]
	v_mfma_f32_16x16x32_bf16 v[90:93], v[150:153], v[194:197], v[90:93]
	v_mfma_f32_16x16x32_bf16 v[86:89], v[142:145], v[202:205], v[86:89]
	v_mfma_f32_16x16x32_bf16 v[82:85], v[150:153], v[202:205], v[82:85]
	s_setprio 0
	s_barrier
	s_mov_b32 m0, s23
	v_lshl_add_u64 v[222:223], s[28:29], 0, v[130:131]
	ds_read_b128 v[206:209], v161
	ds_read_b128 v[210:213], v162
	ds_read_b128 v[214:217], v163
	ds_read_b128 v[218:221], v164
	global_load_lds_dwordx4 v[222:223], off
	v_lshl_add_u64 v[224:225], s[28:29], 0, v[132:133]
	s_mov_b32 m0, s25
	s_nop 0
	global_load_lds_dwordx4 v[224:225], off
	s_barrier
	s_waitcnt lgkmcnt(0)
	s_setprio 1
	s_waitcnt lgkmcnt(0)
	v_mfma_f32_16x16x32_bf16 v[118:121], v[206:209], v[174:177], v[118:121]
	v_mfma_f32_16x16x32_bf16 v[114:117], v[214:217], v[174:177], v[114:117]
	v_mfma_f32_16x16x32_bf16 v[102:105], v[206:209], v[182:185], v[102:105]
	v_mfma_f32_16x16x32_bf16 v[94:97], v[214:217], v[182:185], v[94:97]
	v_mfma_f32_16x16x32_bf16 v[78:81], v[206:209], v[190:193], v[78:81]
	v_mfma_f32_16x16x32_bf16 v[74:77], v[214:217], v[190:193], v[74:77]
	v_mfma_f32_16x16x32_bf16 v[70:73], v[206:209], v[198:201], v[70:73]
	v_mfma_f32_16x16x32_bf16 v[66:69], v[214:217], v[198:201], v[66:69]
	v_mfma_f32_16x16x32_bf16 v[118:121], v[210:213], v[178:181], v[118:121]
	v_mfma_f32_16x16x32_bf16 v[114:117], v[218:221], v[178:181], v[114:117]
	v_mfma_f32_16x16x32_bf16 v[102:105], v[210:213], v[186:189], v[102:105]
	v_mfma_f32_16x16x32_bf16 v[94:97], v[218:221], v[186:189], v[94:97]
	v_mfma_f32_16x16x32_bf16 v[78:81], v[210:213], v[194:197], v[78:81]
	v_mfma_f32_16x16x32_bf16 v[74:77], v[218:221], v[194:197], v[74:77]
	v_mfma_f32_16x16x32_bf16 v[70:73], v[210:213], v[202:205], v[70:73]
	v_mfma_f32_16x16x32_bf16 v[66:69], v[218:221], v[202:205], v[66:69]
	s_setprio 0
	s_mov_b32 m0, s38
	v_lshl_add_u64 v[226:227], s[30:31], 0, v[130:131]
	s_barrier
	ds_read_b128 v[174:177], v155 offset:16384
	ds_read_b128 v[178:181], v155 offset:17408
	ds_read_b128 v[182:185], v155 offset:18432
	ds_read_b128 v[186:189], v155 offset:19456
	ds_read_b128 v[190:193], v155 offset:20480
	ds_read_b128 v[194:197], v155 offset:21504
	ds_read_b128 v[198:201], v155 offset:22528
	ds_read_b128 v[202:205], v155 offset:23552
	global_load_lds_dwordx4 v[226:227], off
	v_lshl_add_u64 v[228:229], s[30:31], 0, v[132:133]
	s_mov_b32 m0, s39
	s_nop 0
	global_load_lds_dwordx4 v[228:229], off
	s_barrier
	s_waitcnt lgkmcnt(0)
	s_setprio 1
	s_waitcnt lgkmcnt(0)
	v_mfma_f32_16x16x32_bf16 v[62:65], v[138:141], v[174:177], v[62:65]
	v_mfma_f32_16x16x32_bf16 v[58:61], v[146:149], v[174:177], v[58:61]
	v_mfma_f32_16x16x32_bf16 v[46:49], v[138:141], v[182:185], v[46:49]
	v_mfma_f32_16x16x32_bf16 v[42:45], v[146:149], v[182:185], v[42:45]
	v_mfma_f32_16x16x32_bf16 v[30:33], v[138:141], v[190:193], v[30:33]
	v_mfma_f32_16x16x32_bf16 v[26:29], v[146:149], v[190:193], v[26:29]
	v_mfma_f32_16x16x32_bf16 v[14:17], v[138:141], v[198:201], v[14:17]
	v_mfma_f32_16x16x32_bf16 v[10:13], v[146:149], v[198:201], v[10:13]
	v_mfma_f32_16x16x32_bf16 v[62:65], v[142:145], v[178:181], v[62:65]
	v_mfma_f32_16x16x32_bf16 v[58:61], v[150:153], v[178:181], v[58:61]
	v_mfma_f32_16x16x32_bf16 v[46:49], v[142:145], v[186:189], v[46:49]
	v_mfma_f32_16x16x32_bf16 v[42:45], v[150:153], v[186:189], v[42:45]
	v_mfma_f32_16x16x32_bf16 v[30:33], v[142:145], v[194:197], v[30:33]
	v_mfma_f32_16x16x32_bf16 v[26:29], v[150:153], v[194:197], v[26:29]
	v_mfma_f32_16x16x32_bf16 v[14:17], v[142:145], v[202:205], v[14:17]
	v_mfma_f32_16x16x32_bf16 v[10:13], v[150:153], v[202:205], v[10:13]
	s_setprio 0
	s_barrier
; #define PG8_STAGE(bufoff, gbase, voff) do { _Pragma("unroll") for (int _i = 0; _i < 2; ++_i) \
;         __builtin_amdgcn_global_load_lds((const unsigned*)((const char*)(gbase) + (voff)[_i]), (PG8_LAS unsigned*)(lds + (bufoff) + ldsw + _i * 8192), 16, 0, 0); } while (0)
; #define PG8_LDA(dst, b, h) do { _Pragma("unroll") for (int m = 0; m < 4; ++m) _Pragma("unroll") for (int k = 0; k < 2; ++k) dst[m][k] = *(const PG8_LAS bf16x8*)(lds + PG8_SA(b, h) + aoff + m * 2048 + k * 1024); } while (0)
; #define PG8_LDB(dst, b, h) do { _Pragma("unroll") for (int n = 0; n < 2; ++n) _Pragma("unroll") for (int k = 0; k < 2; ++k) dst[n][k] = *(const PG8_LAS bf16x8*)(lds + PG8_SB(b, h) + boff + n * 2048 + k * 1024); } while (0)
; #define PG8_MMA(ai, bj, At, Bt) do { __builtin_amdgcn_s_setprio(1); _Pragma("unroll") for (int m = 0; m < 4; ++m) _Pragma("unroll") for (int n = 0; n < 2; ++n) _Pragma("unroll") for (int k = 0; k < 2; ++k) \
;         acc[ai][bj][m][n] = __builtin_amdgcn_mfma_f32_16x16x32_bf16(Bt[n][k], At[m][k], acc[ai][bj][m][n], 0, 0, 0); __builtin_amdgcn_s_setprio(0); } while (0)
; #define PG8_WAIT_V(n) asm volatile("s_waitcnt vmcnt(" #n ")" ::: "memory")
; #define PG8_WAIT_L(n) asm volatile("s_waitcnt lgkmcnt(" #n ")" ::: "memory")
; #define PG8_BAR __builtin_amdgcn_s_barrier()
; #define PG8_SCHED __builtin_amdgcn_sched_barrier(0)
; template <class Epi, class Sched>
; __device__ __forceinline__ void gemm_phase(PG8_LAS unsigned char* lds, const Gemm g, const Sched& S, const Epi& E) {
;     ...
;             PG8_STAGE(PG8_SB(0, 1), b2 + hstep, voffB);
;             PG8_WAIT_V(6); PG8_BAR; PG8_MMA(1, 1, At, B1); PG8_BAR;
;             PG8_LDB(B0, 1, 0); PG8_SCHED; PG8_LDA(At, 1, 0); PG8_STAGE(PG8_SA(0, 1), a2 + hstep, voffA);
;             PG8_WAIT_L(8); PG8_BAR; PG8_WAIT_L(0); PG8_MMA(0, 0, At, B0); PG8_BAR; PG8_SCHED;
;             PG8_LDB(B1, 1, 1); PG8_STAGE(PG8_SB(1, 0), b3, voffB);
;             PG8_BAR; PG8_WAIT_L(0); PG8_MMA(0, 1, At, B1); PG8_BAR;
;             PG8_LDA(At, 1, 1); PG8_STAGE(PG8_SA(1, 0), a3, voffA);
;             PG8_BAR; PG8_WAIT_L(0); PG8_MMA(1, 0, At, B0); PG8_BAR; PG8_SCHED;
;             PG8_STAGE(PG8_SB(1, 1), b3 + hstep, voffB);
;             PG8_WAIT_V(6); PG8_BAR; PG8_MMA(1, 1, At, B1); PG8_BAR;
	s_add_u32 s62, s28, 0x20000
	s_addc_u32 s63, s29, 0
	s_mov_b32 m0, s40
	v_lshl_add_u64 v[138:139], s[62:63], 0, v[130:131]
	global_load_lds_dwordx4 v[138:139], off
	v_lshl_add_u64 v[138:139], s[62:63], 0, v[132:133]
	s_mov_b32 m0, s41
	s_nop 0
	global_load_lds_dwordx4 v[138:139], off
	s_waitcnt vmcnt(6)
	s_barrier
	s_setprio 1
	v_mfma_f32_16x16x32_bf16 v[54:57], v[206:209], v[174:177], v[54:57]
	v_mfma_f32_16x16x32_bf16 v[50:53], v[214:217], v[174:177], v[50:53]
	v_mfma_f32_16x16x32_bf16 v[38:41], v[206:209], v[182:185], v[38:41]
	v_mfma_f32_16x16x32_bf16 v[34:37], v[214:217], v[182:185], v[34:37]
	v_mfma_f32_16x16x32_bf16 v[22:25], v[206:209], v[190:193], v[22:25]
	v_mfma_f32_16x16x32_bf16 v[18:21], v[214:217], v[190:193], v[18:21]
	v_mfma_f32_16x16x32_bf16 v[6:9], v[206:209], v[198:201], v[6:9]
	v_mfma_f32_16x16x32_bf16 v[2:5], v[214:217], v[198:201], v[2:5]
	v_mfma_f32_16x16x32_bf16 v[54:57], v[210:213], v[178:181], v[54:57]
	v_mfma_f32_16x16x32_bf16 v[50:53], v[218:221], v[178:181], v[50:53]
	v_mfma_f32_16x16x32_bf16 v[38:41], v[210:213], v[186:189], v[38:41]
	v_mfma_f32_16x16x32_bf16 v[34:37], v[218:221], v[186:189], v[34:37]
	v_mfma_f32_16x16x32_bf16 v[22:25], v[210:213], v[194:197], v[22:25]
	v_mfma_f32_16x16x32_bf16 v[18:21], v[218:221], v[194:197], v[18:21]
	v_mfma_f32_16x16x32_bf16 v[6:9], v[210:213], v[202:205], v[6:9]
	v_mfma_f32_16x16x32_bf16 v[2:5], v[218:221], v[202:205], v[2:5]
	s_setprio 0
	s_barrier
	ds_read_b128 v[138:141], v165
	ds_read_b128 v[142:145], v166
	ds_read_b128 v[146:149], v167
	ds_read_b128 v[150:153], v168
	s_add_u32 s30, s30, 0x20000
	s_addc_u32 s31, s31, 0
	s_mov_b32 m0, s42
	v_lshl_add_u64 v[206:207], s[30:31], 0, v[130:131]
	ds_read_b128 v[174:177], v155 offset:32768
	ds_read_b128 v[178:181], v155 offset:33792
	ds_read_b128 v[182:185], v155 offset:34816
	ds_read_b128 v[186:189], v155 offset:35840
	ds_read_b128 v[190:193], v155 offset:36864
	ds_read_b128 v[194:197], v155 offset:37888
	ds_read_b128 v[198:201], v155 offset:38912
	ds_read_b128 v[202:205], v155 offset:39936
	global_load_lds_dwordx4 v[206:207], off
	v_lshl_add_u64 v[206:207], s[30:31], 0, v[132:133]
	s_mov_b32 m0, s43
	s_nop 0
	global_load_lds_dwordx4 v[206:207], off
	s_waitcnt lgkmcnt(8)
	s_barrier
	s_waitcnt lgkmcnt(0)
	s_setprio 1
	s_waitcnt lgkmcnt(0)
	v_mfma_f32_16x16x32_bf16 v[126:129], v[138:141], v[174:177], v[126:129]
	v_mfma_f32_16x16x32_bf16 v[122:125], v[146:149], v[174:177], v[122:125]
	v_mfma_f32_16x16x32_bf16 v[110:113], v[138:141], v[182:185], v[110:113]
	v_mfma_f32_16x16x32_bf16 v[106:109], v[146:149], v[182:185], v[106:109]
	v_mfma_f32_16x16x32_bf16 v[98:101], v[138:141], v[190:193], v[98:101]
	v_mfma_f32_16x16x32_bf16 v[90:93], v[146:149], v[190:193], v[90:93]
	v_mfma_f32_16x16x32_bf16 v[86:89], v[138:141], v[198:201], v[86:89]
	v_mfma_f32_16x16x32_bf16 v[82:85], v[146:149], v[198:201], v[82:85]
	v_mfma_f32_16x16x32_bf16 v[126:129], v[142:145], v[178:181], v[126:129]
	v_mfma_f32_16x16x32_bf16 v[122:125], v[150:153], v[178:181], v[122:125]
	v_mfma_f32_16x16x32_bf16 v[110:113], v[142:145], v[186:189], v[110:113]
	v_mfma_f32_16x16x32_bf16 v[106:109], v[150:153], v[186:189], v[106:109]
	v_mfma_f32_16x16x32_bf16 v[98:101], v[142:145], v[194:197], v[98:101]
	v_mfma_f32_16x16x32_bf16 v[90:93], v[150:153], v[194:197], v[90:93]
	v_mfma_f32_16x16x32_bf16 v[86:89], v[142:145], v[202:205], v[86:89]
	v_mfma_f32_16x16x32_bf16 v[82:85], v[150:153], v[202:205], v[82:85]
	s_setprio 0
	s_barrier
	s_mov_b32 m0, s44
	v_lshl_add_u64 v[222:223], v[222:223], 0, s[6:7]
	ds_read_b128 v[206:209], v169
	ds_read_b128 v[210:213], v170
	ds_read_b128 v[214:217], v171
	ds_read_b128 v[218:221], v172
	global_load_lds_dwordx4 v[222:223], off
	v_lshl_add_u64 v[222:223], v[224:225], 0, s[6:7]
	s_mov_b32 m0, s45
	s_nop 0
	global_load_lds_dwordx4 v[222:223], off
	s_barrier
	s_waitcnt lgkmcnt(0)
	s_setprio 1
	s_waitcnt lgkmcnt(0)
	v_mfma_f32_16x16x32_bf16 v[118:121], v[206:209], v[174:177], v[118:121]
	v_mfma_f32_16x16x32_bf16 v[114:117], v[214:217], v[174:177], v[114:117]
	v_mfma_f32_16x16x32_bf16 v[102:105], v[206:209], v[182:185], v[102:105]
	v_mfma_f32_16x16x32_bf16 v[94:97], v[214:217], v[182:185], v[94:97]
	v_mfma_f32_16x16x32_bf16 v[78:81], v[206:209], v[190:193], v[78:81]
	v_mfma_f32_16x16x32_bf16 v[74:77], v[214:217], v[190:193], v[74:77]
	v_mfma_f32_16x16x32_bf16 v[70:73], v[206:209], v[198:201], v[70:73]
	v_mfma_f32_16x16x32_bf16 v[66:69], v[214:217], v[198:201], v[66:69]
	v_mfma_f32_16x16x32_bf16 v[118:121], v[210:213], v[178:181], v[118:121]
	v_mfma_f32_16x16x32_bf16 v[114:117], v[218:221], v[178:181], v[114:117]
	v_mfma_f32_16x16x32_bf16 v[102:105], v[210:213], v[186:189], v[102:105]
	v_mfma_f32_16x16x32_bf16 v[94:97], v[218:221], v[186:189], v[94:97]
	v_mfma_f32_16x16x32_bf16 v[78:81], v[210:213], v[194:197], v[78:81]
	v_mfma_f32_16x16x32_bf16 v[74:77], v[218:221], v[194:197], v[74:77]
	v_mfma_f32_16x16x32_bf16 v[70:73], v[210:213], v[202:205], v[70:73]
	v_mfma_f32_16x16x32_bf16 v[66:69], v[218:221], v[202:205], v[66:69]
	s_setprio 0
	s_mov_b32 m0, s46
	v_lshl_add_u64 v[222:223], v[226:227], 0, s[6:7]
	s_barrier
	ds_read_b128 v[174:177], v155 offset:49152
	ds_read_b128 v[178:181], v155 offset:50176
	ds_read_b128 v[182:185], v155 offset:51200
	ds_read_b128 v[186:189], v155 offset:52224
	ds_read_b128 v[190:193], v155 offset:53248
	ds_read_b128 v[194:197], v155 offset:54272
	ds_read_b128 v[198:201], v155 offset:55296
	ds_read_b128 v[202:205], v155 offset:56320
	global_load_lds_dwordx4 v[222:223], off
	v_lshl_add_u64 v[222:223], v[228:229], 0, s[6:7]
	s_mov_b32 m0, s47
	s_nop 0
	global_load_lds_dwordx4 v[222:223], off
	s_barrier
; #define PG8_STAGE(bufoff, gbase, voff) do { _Pragma("unroll") for (int _i = 0; _i < 2; ++_i) \
;         __builtin_amdgcn_global_load_lds((const unsigned*)((const char*)(gbase) + (voff)[_i]), (PG8_LAS unsigned*)(lds + (bufoff) + ldsw + _i * 8192), 16, 0, 0); } while (0)
; #define PG8_LDA(dst, b, h) do { _Pragma("unroll") for (int m = 0; m < 4; ++m) _Pragma("unroll") for (int k = 0; k < 2; ++k) dst[m][k] = *(const PG8_LAS bf16x8*)(lds + PG8_SA(b, h) + aoff + m * 2048 + k * 1024); } while (0)
; #define PG8_LDB(dst, b, h) do { _Pragma("unroll") for (int n = 0; n < 2; ++n) _Pragma("unroll") for (int k = 0; k < 2; ++k) dst[n][k] = *(const PG8_LAS bf16x8*)(lds + PG8_SB(b, h) + boff + n * 2048 + k * 1024); } while (0)
; #define PG8_WAIT_V(n) asm volatile("s_waitcnt vmcnt(" #n ")" ::: "memory")
; template <class Epi, class Sched>
; __device__ __forceinline__ void gemm_phase(PG8_LAS unsigned char* lds, const Gemm g, const Sched& S, const Epi& E) {
;     ...
;             PG8_WAIT_V(6); PG8_BAR; PG8_MMA(1, 1, At, B1); PG8_BAR;
;             PG8_LDB(B0, 1, 0); PG8_SCHED; PG8_LDA(At, 1, 0); PG8_STAGE(PG8_SA(0, 1), a2 + hstep, voffA);
;             PG8_WAIT_L(8); PG8_BAR; PG8_WAIT_L(0); PG8_MMA(0, 0, At, B0); PG8_BAR; PG8_SCHED;
;             PG8_LDB(B1, 1, 1); PG8_STAGE(PG8_SB(1, 0), b3, voffB);
;             PG8_BAR; PG8_WAIT_L(0); PG8_MMA(0, 1, At, B1); PG8_BAR;
;             PG8_LDA(At, 1, 1); PG8_STAGE(PG8_SA(1, 0), a3, voffA);
;             PG8_BAR; PG8_WAIT_L(0); PG8_MMA(1, 0, At, B0); PG8_BAR; PG8_SCHED;
;             PG8_STAGE(PG8_SB(1, 1), b3 + hstep, voffB);
;             PG8_WAIT_V(6); PG8_BAR; PG8_MMA(1, 1, At, B1); PG8_BAR;
;         }
;         E(acc, cur, wr, wc, fr, fq);
;   __device__ __forceinline__ void operator()(const acc8_t& acc, const pg8::Unit& u, int wr, int wc, int fr, int fq) const {
;     const u16* GB = (const u16*)(ws + OFF_GB); u16* M = (u16*)(ws + OFF_M);
; #pragma unroll
;     for (int ai = 0; ai < 2; ai++)
; #pragma unroll
;       for (int m = 0; m < 4; m++) {
;         const size_t token = EPI_TOKEN(u, ai, m);
; #pragma unroll
;         for (int bj = 0; bj < 2; bj++)
; #pragma unroll
;           for (int n = 0; n < 2; n++) {
;             const int f = EPI_COL(u, bj, n);
;             const uint2 gb = *(const uint2*)(GB + token * 1024 + f);
;             const uint2 mo = *(const uint2*)(M + token * 1024 + f);
	s_waitcnt lgkmcnt(0)
	s_setprio 1
	s_waitcnt lgkmcnt(0)
	v_mfma_f32_16x16x32_bf16 v[62:65], v[138:141], v[174:177], v[62:65]
	v_mfma_f32_16x16x32_bf16 v[58:61], v[146:149], v[174:177], v[58:61]
	v_mfma_f32_16x16x32_bf16 v[46:49], v[138:141], v[182:185], v[46:49]
	v_mfma_f32_16x16x32_bf16 v[42:45], v[146:149], v[182:185], v[42:45]
	v_mfma_f32_16x16x32_bf16 v[30:33], v[138:141], v[190:193], v[30:33]
	v_mfma_f32_16x16x32_bf16 v[26:29], v[146:149], v[190:193], v[26:29]
	v_mfma_f32_16x16x32_bf16 v[14:17], v[138:141], v[198:201], v[14:17]
	v_mfma_f32_16x16x32_bf16 v[10:13], v[146:149], v[198:201], v[10:13]
	v_mfma_f32_16x16x32_bf16 v[62:65], v[142:145], v[178:181], v[62:65]
	v_mfma_f32_16x16x32_bf16 v[58:61], v[150:153], v[178:181], v[58:61]
	v_mfma_f32_16x16x32_bf16 v[46:49], v[142:145], v[186:189], v[46:49]
	v_mfma_f32_16x16x32_bf16 v[42:45], v[150:153], v[186:189], v[42:45]
	v_mfma_f32_16x16x32_bf16 v[30:33], v[142:145], v[194:197], v[30:33]
	v_mfma_f32_16x16x32_bf16 v[26:29], v[150:153], v[194:197], v[26:29]
	v_mfma_f32_16x16x32_bf16 v[14:17], v[142:145], v[202:205], v[14:17]
	v_mfma_f32_16x16x32_bf16 v[10:13], v[150:153], v[202:205], v[10:13]
	s_setprio 0
	s_barrier
	s_add_u32 s28, s28, 0x20080
	s_addc_u32 s29, s29, 0
	s_mov_b32 m0, s48
	v_lshl_add_u64 v[138:139], s[28:29], 0, v[130:131]
	global_load_lds_dwordx4 v[138:139], off
	v_lshl_add_u64 v[138:139], s[28:29], 0, v[132:133]
	s_mov_b32 m0, s49
	s_nop 0
	global_load_lds_dwordx4 v[138:139], off
	s_waitcnt vmcnt(6)
	s_barrier
	s_setprio 1
	v_mfma_f32_16x16x32_bf16 v[54:57], v[206:209], v[174:177], v[54:57]
	v_mfma_f32_16x16x32_bf16 v[50:53], v[214:217], v[174:177], v[50:53]
	v_mfma_f32_16x16x32_bf16 v[38:41], v[206:209], v[182:185], v[38:41]
	v_mfma_f32_16x16x32_bf16 v[34:37], v[214:217], v[182:185], v[34:37]
	v_mfma_f32_16x16x32_bf16 v[22:25], v[206:209], v[190:193], v[22:25]
	v_mfma_f32_16x16x32_bf16 v[18:21], v[214:217], v[190:193], v[18:21]
	v_mfma_f32_16x16x32_bf16 v[6:9], v[206:209], v[198:201], v[6:9]
	v_mfma_f32_16x16x32_bf16 v[2:5], v[214:217], v[198:201], v[2:5]
	v_mfma_f32_16x16x32_bf16 v[54:57], v[210:213], v[178:181], v[54:57]
	v_mfma_f32_16x16x32_bf16 v[50:53], v[218:221], v[178:181], v[50:53]
	v_mfma_f32_16x16x32_bf16 v[38:41], v[210:213], v[186:189], v[38:41]
	v_mfma_f32_16x16x32_bf16 v[34:37], v[218:221], v[186:189], v[34:37]
	v_mfma_f32_16x16x32_bf16 v[22:25], v[210:213], v[194:197], v[22:25]
	v_mfma_f32_16x16x32_bf16 v[18:21], v[218:221], v[194:197], v[18:21]
	v_mfma_f32_16x16x32_bf16 v[6:9], v[210:213], v[202:205], v[6:9]
	v_mfma_f32_16x16x32_bf16 v[2:5], v[218:221], v[202:205], v[2:5]
	s_setprio 0
	s_add_i32 s61, s61, 2
	s_add_u32 s26, s26, 0x100
	s_addc_u32 s27, s27, 0
	s_add_u32 s59, s59, 0x100
	s_addc_u32 s60, s60, 0
	s_cmp_gt_u32 s61, 5
	s_barrier
	s_cbranch_scc0 .LBB0_713
	s_cmp_eq_u32 s0, 16
	s_cbranch_scc0 .Lp4r_go
	s_cmp_eq_u32 s50, 2
	s_cbranch_scc0 .Lp4r_go
	s_and_b32 vcc_hi, s94, 7
	s_lshl_b32 vcc_hi, vcc_hi, 8
	s_add_i32 vcc_hi, vcc_hi, 0xb23400
	v_mov_b32_e32 v138, vcc_hi
	v_mov_b32_e32 v139, 0
	s_movk_i32 vcc_lo, 0x800
	s_mov_b64 exec, 1
.Lp4r_spin:
	global_atomic_add v140, v138, v139, s[88:89] sc0
	s_waitcnt vmcnt(0)
	v_readfirstlane_b32 vcc_hi, v140
	s_cmp_lg_u32 vcc_hi, 0
	s_cbranch_scc1 .Lp4r_acq
	s_sleep 2
	s_sub_i32 vcc_lo, vcc_lo, 1
	s_cmp_lg_u32 vcc_lo, 0
	s_cbranch_scc1 .Lp4r_spin
.Lp4r_acq:
	s_mov_b64 exec, -1
	buffer_inv sc1
	s_waitcnt vmcnt(0)
.Lp4r_go:
	v_lshl_add_u32 v138, s24, 8, v154
	v_lshl_or_b32 v140, s22, 8, v156
	v_ashrrev_i32_e32 v139, 31, v138
	v_lshlrev_b64 v[142:143], 11, v[138:139]
	v_ashrrev_i32_e32 v141, 31, v140
	v_lshl_add_u64 v[144:145], s[8:9], 0, v[142:143]
	v_lshl_add_u64 v[142:143], s[10:11], 0, v[142:143]
	v_lshlrev_b64 v[140:141], 1, v[140:141]
	v_lshl_add_u64 v[146:147], v[142:143], 0, v[140:141]
	v_lshl_add_u64 v[144:145], v[144:145], 0, v[140:141]
	global_load_dwordx2 v[174:175], v[146:147], off
	global_load_dwordx2 v[176:177], v[144:145], off
	global_load_dwordx2 v[178:179], v[146:147], off offset:32
	global_load_dwordx2 v[180:181], v[144:145], off offset:32
	global_load_dwordx2 v[182:183], v[146:147], off offset:256
	global_load_dwordx2 v[184:185], v[144:145], off offset:256
	global_load_dwordx2 v[186:187], v[146:147], off offset:288
	global_load_dwordx2 v[188:189], v[144:145], off offset:288
	v_or_b32_e32 v142, 16, v138
	v_ashrrev_i32_e32 v143, 31, v142
	v_lshlrev_b64 v[142:143], 11, v[142:143]
	v_lshl_add_u64 v[144:145], s[8:9], 0, v[142:143]
	v_lshl_add_u64 v[142:143], s[10:11], 0, v[142:143]
	v_lshl_add_u64 v[150:151], v[144:145], 0, v[140:141]
	v_lshl_add_u64 v[144:145], v[142:143], 0, v[140:141]
	global_load_dwordx2 v[190:191], v[144:145], off
	global_load_dwordx2 v[192:193], v[150:151], off
	v_or_b32_e32 v142, 32, v138
	v_ashrrev_i32_e32 v143, 31, v142
	v_lshlrev_b64 v[142:143], 11, v[142:143]
	v_lshl_add_u64 v[148:149], s[8:9], 0, v[142:143]
	v_lshl_add_u64 v[142:143], s[10:11], 0, v[142:143]
	v_lshl_add_u64 v[148:149], v[148:149], 0, v[140:141]
	v_lshl_add_u64 v[142:143], v[142:143], 0, v[140:141]
	global_load_dwordx2 v[194:195], v[150:151], off offset:32
	global_load_dwordx2 v[196:197], v[150:151], off offset:256
	global_load_dwordx2 v[198:199], v[150:151], off offset:288
	global_load_dwordx2 v[200:201], v[144:145], off offset:32
	global_load_dwordx2 v[202:203], v[144:145], off offset:256
	global_load_dwordx2 v[204:205], v[144:145], off offset:288
	s_nop 0
	global_load_dwordx2 v[150:151], v[148:149], off
	global_load_dwordx2 v[152:153], v[142:143], off
	s_and_b64 vcc, exec, s[16:17]
	s_mov_b32 s22, s12
	s_mov_b32 s24, s14
	s_mov_b64 s[28:29], s[20:21]
	s_mov_b64 s[26:27], s[18:19]
	s_waitcnt vmcnt(0)
; __device__ __forceinline__ float bflo(uint32_t v) { return __uint_as_float(v << 16); }
; __device__ __forceinline__ float bfhi(uint32_t v) { return __uint_as_float(v & 0xFFFF0000u); }
;   __device__ __forceinline__ void operator()(const acc8_t& acc, const pg8::Unit& u, int wr, int wc, int fr, int fq) const {
;     const u16* GB = (const u16*)(ws + OFF_GB); u16* M = (u16*)(ws + OFF_M);
; #pragma unroll
;     for (int ai = 0; ai < 2; ai++)
; #pragma unroll
;       for (int m = 0; m < 4; m++) {
;         const size_t token = EPI_TOKEN(u, ai, m);
; #pragma unroll
;         for (int bj = 0; bj < 2; bj++)
; #pragma unroll
;           for (int n = 0; n < 2; n++) {
;             const int f = EPI_COL(u, bj, n);
;             const uint2 gb = *(const uint2*)(GB + token * 1024 + f);
;             const uint2 mo = *(const uint2*)(M + token * 1024 + f);
;             uint2 o;
;             o.x = pack2(bflo(mo.x) + bflo(gb.x) * acc[ai][bj][m][n][0], bfhi(mo.x) + bfhi(gb.x) * acc[ai][bj][m][n][1]);
;             o.y = pack2(bflo(mo.y) + bflo(gb.y) * acc[ai][bj][m][n][2], bfhi(mo.y) + bfhi(gb.y) * acc[ai][bj][m][n][3]);
;             *(uint2*)(M + token * 1024 + f) = o;
;           }
;       }
;   }
	v_lshlrev_b32_e32 v206, 16, v174
	v_lshlrev_b32_e32 v208, 16, v176
	v_and_b32_e32 v207, 0xffff0000, v174
	v_and_b32_e32 v209, 0xffff0000, v176
	v_lshlrev_b32_e32 v174, 16, v175
	v_lshlrev_b32_e32 v176, 16, v177
	v_and_b32_e32 v175, 0xffff0000, v175
	v_and_b32_e32 v177, 0xffff0000, v177
	v_lshlrev_b32_e32 v218, 16, v186
	v_lshlrev_b32_e32 v220, 16, v188
	v_and_b32_e32 v219, 0xffff0000, v186
	v_and_b32_e32 v221, 0xffff0000, v188
	v_lshlrev_b32_e32 v186, 16, v187
	v_lshlrev_b32_e32 v188, 16, v189
	v_and_b32_e32 v187, 0xffff0000, v187
	v_and_b32_e32 v189, 0xffff0000, v189
	v_lshlrev_b32_e32 v210, 16, v178
	v_lshlrev_b32_e32 v212, 16, v180
	v_and_b32_e32 v211, 0xffff0000, v178
	v_and_b32_e32 v213, 0xffff0000, v180
	v_lshlrev_b32_e32 v178, 16, v179
	v_lshlrev_b32_e32 v180, 16, v181
	v_and_b32_e32 v179, 0xffff0000, v179
	v_and_b32_e32 v181, 0xffff0000, v181
	v_lshlrev_b32_e32 v214, 16, v182
	v_lshlrev_b32_e32 v216, 16, v184
	v_and_b32_e32 v215, 0xffff0000, v182
	v_and_b32_e32 v217, 0xffff0000, v184
	v_lshlrev_b32_e32 v182, 16, v183
	v_lshlrev_b32_e32 v184, 16, v185
	v_and_b32_e32 v183, 0xffff0000, v183
	v_and_b32_e32 v185, 0xffff0000, v185
	v_pk_fma_f32 v[126:127], v[126:127], v[208:209], v[206:207]
	v_pk_fma_f32 v[128:129], v[128:129], v[176:177], v[174:175]
	v_pk_fma_f32 v[114:115], v[114:115], v[220:221], v[218:219]
	v_pk_fma_f32 v[116:117], v[116:117], v[188:189], v[186:187]
	v_pk_fma_f32 v[122:123], v[122:123], v[212:213], v[210:211]
	v_pk_fma_f32 v[124:125], v[124:125], v[180:181], v[178:179]
	v_pk_fma_f32 v[118:119], v[118:119], v[216:217], v[214:215]
	v_pk_fma_f32 v[120:121], v[120:121], v[184:185], v[182:183]
	v_cvt_pk_bf16_f32 v126, v126, v127
	v_cvt_pk_bf16_f32 v127, v128, v129
	v_cvt_pk_bf16_f32 v114, v114, v115
	v_cvt_pk_bf16_f32 v115, v116, v117
	v_cvt_pk_bf16_f32 v122, v122, v123
	v_cvt_pk_bf16_f32 v123, v124, v125
	v_cvt_pk_bf16_f32 v118, v118, v119
	v_cvt_pk_bf16_f32 v119, v120, v121
	global_store_dwordx2 v[146:147], v[126:127], off
	global_store_dwordx2 v[146:147], v[122:123], off offset:32
	global_store_dwordx2 v[146:147], v[118:119], off offset:256
	global_store_dwordx2 v[146:147], v[114:115], off offset:288
	global_load_dwordx2 v[118:119], v[142:143], off offset:32
	s_nop 0
	global_load_dwordx2 v[120:121], v[148:149], off offset:32
	v_lshlrev_b32_e32 v114, 16, v190
	v_lshlrev_b32_e32 v116, 16, v192
	v_and_b32_e32 v115, 0xffff0000, v190
	v_and_b32_e32 v117, 0xffff0000, v192
	v_pk_fma_f32 v[110:111], v[110:111], v[116:117], v[114:115]
	global_load_dwordx2 v[114:115], v[142:143], off offset:256
	v_cvt_pk_bf16_f32 v116, v110, v111
	v_or_b32_e32 v110, 48, v138
	v_ashrrev_i32_e32 v111, 31, v110
	v_lshlrev_b64 v[110:111], 11, v[110:111]
	v_lshl_add_u64 v[126:127], s[8:9], 0, v[110:111]
	v_lshl_add_u64 v[110:111], s[10:11], 0, v[110:111]
	v_lshl_add_u64 v[110:111], v[110:111], 0, v[140:141]
	v_lshl_add_u64 v[126:127], v[126:127], 0, v[140:141]
	global_load_dwordx2 v[128:129], v[110:111], off
	global_load_dwordx2 v[146:147], v[126:127], off
	v_lshlrev_b32_e32 v122, 16, v191
	v_lshlrev_b32_e32 v124, 16, v193
	v_and_b32_e32 v123, 0xffff0000, v191
	v_and_b32_e32 v125, 0xffff0000, v193
	v_pk_fma_f32 v[112:113], v[112:113], v[124:125], v[122:123]
	s_nop 0
	v_cvt_pk_bf16_f32 v117, v112, v113
	global_store_dwordx2 v[144:145], v[116:117], off
	v_lshlrev_b32_e32 v112, 16, v200
	v_lshlrev_b32_e32 v116, 16, v194
	v_and_b32_e32 v113, 0xffff0000, v200
	v_and_b32_e32 v117, 0xffff0000, v194
	v_pk_fma_f32 v[106:107], v[106:107], v[116:117], v[112:113]
	v_lshlrev_b32_e32 v112, 16, v201
	v_lshlrev_b32_e32 v116, 16, v195
	v_and_b32_e32 v113, 0xffff0000, v201
	v_and_b32_e32 v117, 0xffff0000, v195
	v_pk_fma_f32 v[108:109], v[108:109], v[116:117], v[112:113]
	v_cvt_pk_bf16_f32 v106, v106, v107
	v_cvt_pk_bf16_f32 v107, v108, v109
	global_load_dwordx2 v[122:123], v[110:111], off offset:32
	global_load_dwordx2 v[124:125], v[126:127], off offset:32
	v_lshlrev_b32_e32 v108, 16, v196
	global_store_dwordx2 v[144:145], v[106:107], off offset:32
	v_lshlrev_b32_e32 v106, 16, v202
	v_and_b32_e32 v107, 0xffff0000, v202
	v_and_b32_e32 v109, 0xffff0000, v196
	v_pk_fma_f32 v[102:103], v[102:103], v[108:109], v[106:107]
	v_lshlrev_b32_e32 v106, 16, v203
	v_lshlrev_b32_e32 v108, 16, v197
	v_and_b32_e32 v107, 0xffff0000, v203
	v_and_b32_e32 v109, 0xffff0000, v197
	v_pk_fma_f32 v[104:105], v[104:105], v[108:109], v[106:107]
	v_cvt_pk_bf16_f32 v102, v102, v103
	v_cvt_pk_bf16_f32 v103, v104, v105
	global_store_dwordx2 v[144:145], v[102:103], off offset:256
	v_lshlrev_b32_e32 v102, 16, v204
	v_lshlrev_b32_e32 v104, 16, v198
	v_and_b32_e32 v103, 0xffff0000, v204
	v_and_b32_e32 v105, 0xffff0000, v198
	global_load_dwordx2 v[106:107], v[148:149], off offset:256
	v_pk_fma_f32 v[94:95], v[94:95], v[104:105], v[102:103]
	v_lshlrev_b32_e32 v102, 16, v205
	v_lshlrev_b32_e32 v104, 16, v199
	v_and_b32_e32 v103, 0xffff0000, v205
	v_and_b32_e32 v105, 0xffff0000, v199
	v_pk_fma_f32 v[96:97], v[96:97], v[104:105], v[102:103]
	v_cvt_pk_bf16_f32 v94, v94, v95
	v_cvt_pk_bf16_f32 v95, v96, v97
	v_lshlrev_b32_e32 v96, 16, v152
	v_lshlrev_b32_e32 v104, 16, v150
	v_and_b32_e32 v97, 0xffff0000, v152
	v_and_b32_e32 v105, 0xffff0000, v150
	global_store_dwordx2 v[144:145], v[94:95], off offset:288
	global_load_dwordx2 v[102:103], v[148:149], off offset:288
	v_pk_fma_f32 v[96:97], v[98:99], v[104:105], v[96:97]
	global_load_dwordx2 v[94:95], v[142:143], off offset:288
	v_lshlrev_b32_e32 v98, 16, v153
	v_lshlrev_b32_e32 v104, 16, v151
	v_and_b32_e32 v99, 0xffff0000, v153
	v_and_b32_e32 v105, 0xffff0000, v151
	v_pk_fma_f32 v[98:99], v[100:101], v[104:105], v[98:99]
	v_cvt_pk_bf16_f32 v96, v96, v97
	v_cvt_pk_bf16_f32 v97, v98, v99
	global_store_dwordx2 v[142:143], v[96:97], off
	s_waitcnt vmcnt(0)
; __device__ __forceinline__ float bflo(uint32_t v) { return __uint_as_float(v << 16); }
; __device__ __forceinline__ float bfhi(uint32_t v) { return __uint_as_float(v & 0xFFFF0000u); }
;   __device__ __forceinline__ void operator()(const acc8_t& acc, const pg8::Unit& u, int wr, int wc, int fr, int fq) const {
;     const u16* GB = (const u16*)(ws + OFF_GB); u16* M = (u16*)(ws + OFF_M);
; #pragma unroll
;     for (int ai = 0; ai < 2; ai++)
; #pragma unroll
;       for (int m = 0; m < 4; m++) {
;         const size_t token = EPI_TOKEN(u, ai, m);
; #pragma unroll
;         for (int bj = 0; bj < 2; bj++)
; #pragma unroll
;           for (int n = 0; n < 2; n++) {
;             const int f = EPI_COL(u, bj, n);
;             const uint2 gb = *(const uint2*)(GB + token * 1024 + f);
;             const uint2 mo = *(const uint2*)(M + token * 1024 + f);
;             uint2 o;
;             o.x = pack2(bflo(mo.x) + bflo(gb.x) * acc[ai][bj][m][n][0], bfhi(mo.x) + bfhi(gb.x) * acc[ai][bj][m][n][1]);
;             o.y = pack2(bflo(mo.y) + bflo(gb.y) * acc[ai][bj][m][n][2], bfhi(mo.y) + bfhi(gb.y) * acc[ai][bj][m][n][3]);
;             *(uint2*)(M + token * 1024 + f) = o;
;           }
;       }
;   }
	v_lshlrev_b32_e32 v100, 16, v118
	v_lshlrev_b32_e32 v104, 16, v120
	v_and_b32_e32 v101, 0xffff0000, v118
	v_and_b32_e32 v105, 0xffff0000, v120
	global_load_dwordx2 v[96:97], v[110:111], off offset:256
	global_load_dwordx2 v[98:99], v[126:127], off offset:256
	v_pk_fma_f32 v[90:91], v[90:91], v[104:105], v[100:101]
	v_lshlrev_b32_e32 v100, 16, v119
	v_lshlrev_b32_e32 v104, 16, v121
	v_and_b32_e32 v101, 0xffff0000, v119
	v_and_b32_e32 v105, 0xffff0000, v121
	v_pk_fma_f32 v[92:93], v[92:93], v[104:105], v[100:101]
	v_cvt_pk_bf16_f32 v90, v90, v91
	v_cvt_pk_bf16_f32 v91, v92, v93
	global_store_dwordx2 v[142:143], v[90:91], off offset:32
	global_load_dwordx2 v[90:91], v[110:111], off offset:288
	s_nop 0
	global_load_dwordx2 v[92:93], v[126:127], off offset:288
	v_lshlrev_b32_e32 v104, 16, v128
	v_lshlrev_b32_e32 v108, 16, v146
	v_and_b32_e32 v105, 0xffff0000, v128
	v_and_b32_e32 v109, 0xffff0000, v146
	v_pk_fma_f32 v[86:87], v[86:87], v[108:109], v[104:105]
	v_lshlrev_b32_e32 v104, 16, v129
	v_lshlrev_b32_e32 v108, 16, v147
	v_and_b32_e32 v105, 0xffff0000, v129
	v_and_b32_e32 v109, 0xffff0000, v147
	v_pk_fma_f32 v[88:89], v[88:89], v[108:109], v[104:105]
	v_cvt_pk_bf16_f32 v86, v86, v87
	v_cvt_pk_bf16_f32 v87, v88, v89
	global_store_dwordx2 v[110:111], v[86:87], off
	v_add_u32_e32 v86, 0x80, v138
	v_ashrrev_i32_e32 v87, 31, v86
	v_lshlrev_b64 v[86:87], 11, v[86:87]
	v_lshl_add_u64 v[108:109], s[8:9], 0, v[86:87]
	v_lshl_add_u64 v[86:87], s[10:11], 0, v[86:87]
	v_lshl_add_u64 v[86:87], v[86:87], 0, v[140:141]
	v_lshl_add_u64 v[108:109], v[108:109], 0, v[140:141]
	global_load_dwordx2 v[112:113], v[86:87], off
	global_load_dwordx2 v[116:117], v[108:109], off
	v_lshlrev_b32_e32 v88, 16, v122
	v_lshlrev_b32_e32 v104, 16, v124
	v_and_b32_e32 v89, 0xffff0000, v122
	v_and_b32_e32 v105, 0xffff0000, v124
	v_pk_fma_f32 v[82:83], v[82:83], v[104:105], v[88:89]
	v_lshlrev_b32_e32 v88, 16, v123
	v_lshlrev_b32_e32 v104, 16, v125
	v_and_b32_e32 v89, 0xffff0000, v123
	v_and_b32_e32 v105, 0xffff0000, v125
	v_lshlrev_b32_e32 v100, 16, v114
	v_pk_fma_f32 v[84:85], v[84:85], v[104:105], v[88:89]
	v_and_b32_e32 v101, 0xffff0000, v114
	v_cvt_pk_bf16_f32 v82, v82, v83
	v_cvt_pk_bf16_f32 v83, v84, v85
	global_store_dwordx2 v[110:111], v[82:83], off offset:32
	global_load_dwordx2 v[82:83], v[86:87], off offset:32
	s_nop 0
	global_load_dwordx2 v[84:85], v[108:109], off offset:32
	v_lshlrev_b32_e32 v88, 16, v106
	v_and_b32_e32 v89, 0xffff0000, v106
	v_pk_fma_f32 v[78:79], v[78:79], v[88:89], v[100:101]
	v_lshlrev_b32_e32 v88, 16, v115
	v_lshlrev_b32_e32 v100, 16, v107
	v_and_b32_e32 v89, 0xffff0000, v115
	v_and_b32_e32 v101, 0xffff0000, v107
	v_pk_fma_f32 v[80:81], v[80:81], v[100:101], v[88:89]
	v_cvt_pk_bf16_f32 v78, v78, v79
	v_cvt_pk_bf16_f32 v79, v80, v81
	global_store_dwordx2 v[142:143], v[78:79], off offset:256
	v_lshlrev_b32_e32 v80, 16, v102
	v_and_b32_e32 v81, 0xffff0000, v102
	v_lshlrev_b32_e32 v78, 16, v94
	v_and_b32_e32 v79, 0xffff0000, v94
	v_pk_fma_f32 v[74:75], v[74:75], v[80:81], v[78:79]
	v_lshlrev_b32_e32 v78, 16, v95
	v_lshlrev_b32_e32 v80, 16, v103
	v_and_b32_e32 v79, 0xffff0000, v95
	v_and_b32_e32 v81, 0xffff0000, v103
	v_pk_fma_f32 v[76:77], v[76:77], v[80:81], v[78:79]
	v_cvt_pk_bf16_f32 v74, v74, v75
	v_cvt_pk_bf16_f32 v75, v76, v77
	global_store_dwordx2 v[142:143], v[74:75], off offset:288
	s_waitcnt vmcnt(0)
	v_lshlrev_b32_e32 v74, 16, v96
	v_lshlrev_b32_e32 v76, 16, v98
	v_and_b32_e32 v75, 0xffff0000, v96
	v_and_b32_e32 v77, 0xffff0000, v98
	v_pk_fma_f32 v[70:71], v[70:71], v[76:77], v[74:75]
	v_lshlrev_b32_e32 v74, 16, v97
	v_lshlrev_b32_e32 v76, 16, v99
	v_and_b32_e32 v75, 0xffff0000, v97
	v_and_b32_e32 v77, 0xffff0000, v99
	v_pk_fma_f32 v[72:73], v[72:73], v[76:77], v[74:75]
	v_cvt_pk_bf16_f32 v70, v70, v71
	v_cvt_pk_bf16_f32 v71, v72, v73
	global_store_dwordx2 v[110:111], v[70:71], off offset:256
	v_lshlrev_b32_e32 v74, 16, v90
	v_lshlrev_b32_e32 v76, 16, v92
	v_and_b32_e32 v75, 0xffff0000, v90
	v_and_b32_e32 v77, 0xffff0000, v92
	global_load_dwordx2 v[70:71], v[86:87], off offset:256
	global_load_dwordx2 v[72:73], v[108:109], off offset:256
	v_pk_fma_f32 v[66:67], v[66:67], v[76:77], v[74:75]
	v_lshlrev_b32_e32 v74, 16, v91
	v_lshlrev_b32_e32 v76, 16, v93
	v_and_b32_e32 v75, 0xffff0000, v91
	v_and_b32_e32 v77, 0xffff0000, v93
	v_pk_fma_f32 v[68:69], v[68:69], v[76:77], v[74:75]
	v_cvt_pk_bf16_f32 v66, v66, v67
	v_cvt_pk_bf16_f32 v67, v68, v69
	global_store_dwordx2 v[110:111], v[66:67], off offset:288
	global_load_dwordx2 v[66:67], v[86:87], off offset:288
	s_nop 0
	global_load_dwordx2 v[68:69], v[108:109], off offset:288
	v_lshlrev_b32_e32 v74, 16, v112
	v_lshlrev_b32_e32 v76, 16, v116
	v_and_b32_e32 v75, 0xffff0000, v112
	v_and_b32_e32 v77, 0xffff0000, v116
	v_pk_fma_f32 v[62:63], v[62:63], v[76:77], v[74:75]
	v_lshlrev_b32_e32 v74, 16, v113
	v_lshlrev_b32_e32 v76, 16, v117
	v_and_b32_e32 v75, 0xffff0000, v113
	v_and_b32_e32 v77, 0xffff0000, v117
	v_pk_fma_f32 v[64:65], v[64:65], v[76:77], v[74:75]
	v_cvt_pk_bf16_f32 v62, v62, v63
	v_cvt_pk_bf16_f32 v63, v64, v65
	global_store_dwordx2 v[86:87], v[62:63], off
	v_add_u32_e32 v62, 0x90, v138
	v_ashrrev_i32_e32 v63, 31, v62
	v_lshlrev_b64 v[62:63], 11, v[62:63]
	v_lshl_add_u64 v[76:77], s[8:9], 0, v[62:63]
	v_lshl_add_u64 v[62:63], s[10:11], 0, v[62:63]
	v_lshl_add_u64 v[62:63], v[62:63], 0, v[140:141]
	v_lshl_add_u64 v[76:77], v[76:77], 0, v[140:141]
	global_load_dwordx2 v[78:79], v[62:63], off
	global_load_dwordx2 v[80:81], v[76:77], off
	v_lshlrev_b32_e32 v64, 16, v82
	v_lshlrev_b32_e32 v74, 16, v84
	v_and_b32_e32 v65, 0xffff0000, v82
	v_and_b32_e32 v75, 0xffff0000, v84
	v_pk_fma_f32 v[58:59], v[58:59], v[74:75], v[64:65]
	v_lshlrev_b32_e32 v64, 16, v83
	v_lshlrev_b32_e32 v74, 16, v85
	v_and_b32_e32 v65, 0xffff0000, v83
	v_and_b32_e32 v75, 0xffff0000, v85
	v_pk_fma_f32 v[60:61], v[60:61], v[74:75], v[64:65]
	v_cvt_pk_bf16_f32 v58, v58, v59
	v_cvt_pk_bf16_f32 v59, v60, v61
	global_store_dwordx2 v[86:87], v[58:59], off offset:32
	global_load_dwordx2 v[58:59], v[62:63], off offset:32
	s_nop 0
	global_load_dwordx2 v[60:61], v[76:77], off offset:32
	s_waitcnt vmcnt(0)
; __device__ __forceinline__ float bflo(uint32_t v) { return __uint_as_float(v << 16); }
; __device__ __forceinline__ float bfhi(uint32_t v) { return __uint_as_float(v & 0xFFFF0000u); }
;   __device__ __forceinline__ void operator()(const acc8_t& acc, const pg8::Unit& u, int wr, int wc, int fr, int fq) const {
;     const u16* GB = (const u16*)(ws + OFF_GB); u16* M = (u16*)(ws + OFF_M);
; #pragma unroll
;     for (int ai = 0; ai < 2; ai++)
; #pragma unroll
;       for (int m = 0; m < 4; m++) {
;         const size_t token = EPI_TOKEN(u, ai, m);
; #pragma unroll
;         for (int bj = 0; bj < 2; bj++)
; #pragma unroll
;           for (int n = 0; n < 2; n++) {
;             const int f = EPI_COL(u, bj, n);
;             const uint2 gb = *(const uint2*)(GB + token * 1024 + f);
;             const uint2 mo = *(const uint2*)(M + token * 1024 + f);
;             uint2 o;
;             o.x = pack2(bflo(mo.x) + bflo(gb.x) * acc[ai][bj][m][n][0], bfhi(mo.x) + bfhi(gb.x) * acc[ai][bj][m][n][1]);
;             o.y = pack2(bflo(mo.y) + bflo(gb.y) * acc[ai][bj][m][n][2], bfhi(mo.y) + bfhi(gb.y) * acc[ai][bj][m][n][3]);
;             *(uint2*)(M + token * 1024 + f) = o;
;           }
;       }
;   }
	v_lshlrev_b32_e32 v64, 16, v70
	v_lshlrev_b32_e32 v74, 16, v72
	v_and_b32_e32 v65, 0xffff0000, v70
	v_and_b32_e32 v75, 0xffff0000, v72
	v_pk_fma_f32 v[54:55], v[54:55], v[74:75], v[64:65]
	v_lshlrev_b32_e32 v64, 16, v71
	v_lshlrev_b32_e32 v70, 16, v73
	v_and_b32_e32 v65, 0xffff0000, v71
	v_and_b32_e32 v71, 0xffff0000, v73
	v_pk_fma_f32 v[56:57], v[56:57], v[70:71], v[64:65]
	v_cvt_pk_bf16_f32 v54, v54, v55
	v_cvt_pk_bf16_f32 v55, v56, v57
	global_store_dwordx2 v[86:87], v[54:55], off offset:256
	v_lshlrev_b32_e32 v64, 16, v66
	v_lshlrev_b32_e32 v70, 16, v68
	v_and_b32_e32 v65, 0xffff0000, v66
	v_and_b32_e32 v71, 0xffff0000, v68
	global_load_dwordx2 v[54:55], v[62:63], off offset:256
	global_load_dwordx2 v[56:57], v[76:77], off offset:256
	v_pk_fma_f32 v[50:51], v[50:51], v[70:71], v[64:65]
	v_lshlrev_b32_e32 v64, 16, v67
	v_lshlrev_b32_e32 v66, 16, v69
	v_and_b32_e32 v65, 0xffff0000, v67
	v_and_b32_e32 v67, 0xffff0000, v69
	v_pk_fma_f32 v[52:53], v[52:53], v[66:67], v[64:65]
	v_cvt_pk_bf16_f32 v50, v50, v51
	v_cvt_pk_bf16_f32 v51, v52, v53
	global_store_dwordx2 v[86:87], v[50:51], off offset:288
	global_load_dwordx2 v[50:51], v[62:63], off offset:288
	s_nop 0
	global_load_dwordx2 v[52:53], v[76:77], off offset:288
	v_lshlrev_b32_e32 v64, 16, v78
	v_lshlrev_b32_e32 v66, 16, v80
	v_and_b32_e32 v65, 0xffff0000, v78
	v_and_b32_e32 v67, 0xffff0000, v80
	v_pk_fma_f32 v[46:47], v[46:47], v[66:67], v[64:65]
	v_lshlrev_b32_e32 v64, 16, v79
	v_lshlrev_b32_e32 v66, 16, v81
	v_and_b32_e32 v65, 0xffff0000, v79
	v_and_b32_e32 v67, 0xffff0000, v81
	v_pk_fma_f32 v[48:49], v[48:49], v[66:67], v[64:65]
	v_cvt_pk_bf16_f32 v46, v46, v47
	v_cvt_pk_bf16_f32 v47, v48, v49
	global_store_dwordx2 v[62:63], v[46:47], off
	v_add_u32_e32 v46, 0xa0, v138
	v_ashrrev_i32_e32 v47, 31, v46
	v_lshlrev_b64 v[46:47], 11, v[46:47]
	v_lshl_add_u64 v[66:67], s[8:9], 0, v[46:47]
	v_lshl_add_u64 v[46:47], s[10:11], 0, v[46:47]
	v_lshlrev_b32_e32 v48, 16, v58
	v_lshlrev_b32_e32 v64, 16, v60
	v_lshl_add_u64 v[46:47], v[46:47], 0, v[140:141]
	v_and_b32_e32 v49, 0xffff0000, v58
	v_and_b32_e32 v65, 0xffff0000, v60
	v_lshl_add_u64 v[66:67], v[66:67], 0, v[140:141]
	global_load_dwordx2 v[68:69], v[46:47], off
	global_load_dwordx2 v[70:71], v[66:67], off
	v_pk_fma_f32 v[42:43], v[42:43], v[64:65], v[48:49]
	v_lshlrev_b32_e32 v48, 16, v59
	v_lshlrev_b32_e32 v58, 16, v61
	v_and_b32_e32 v49, 0xffff0000, v59
	v_and_b32_e32 v59, 0xffff0000, v61
	v_pk_fma_f32 v[44:45], v[44:45], v[58:59], v[48:49]
	v_cvt_pk_bf16_f32 v42, v42, v43
	v_cvt_pk_bf16_f32 v43, v44, v45
	global_store_dwordx2 v[62:63], v[42:43], off offset:32
	global_load_dwordx2 v[42:43], v[46:47], off offset:32
	s_nop 0
	global_load_dwordx2 v[44:45], v[66:67], off offset:32
	s_waitcnt vmcnt(0)
	v_lshlrev_b32_e32 v48, 16, v54
	v_lshlrev_b32_e32 v58, 16, v56
	v_and_b32_e32 v49, 0xffff0000, v54
	v_and_b32_e32 v59, 0xffff0000, v56
	v_pk_fma_f32 v[38:39], v[38:39], v[58:59], v[48:49]
	v_lshlrev_b32_e32 v48, 16, v55
	v_lshlrev_b32_e32 v54, 16, v57
	v_and_b32_e32 v49, 0xffff0000, v55
	v_and_b32_e32 v55, 0xffff0000, v57
	v_pk_fma_f32 v[40:41], v[40:41], v[54:55], v[48:49]
	v_cvt_pk_bf16_f32 v38, v38, v39
	v_cvt_pk_bf16_f32 v39, v40, v41
	global_store_dwordx2 v[62:63], v[38:39], off offset:256
	v_lshlrev_b32_e32 v48, 16, v50
	v_lshlrev_b32_e32 v54, 16, v52
	v_and_b32_e32 v49, 0xffff0000, v50
	v_and_b32_e32 v55, 0xffff0000, v52
	global_load_dwordx2 v[38:39], v[46:47], off offset:256
	global_load_dwordx2 v[40:41], v[66:67], off offset:256
	v_pk_fma_f32 v[34:35], v[34:35], v[54:55], v[48:49]
	v_lshlrev_b32_e32 v48, 16, v51
	v_lshlrev_b32_e32 v50, 16, v53
	v_and_b32_e32 v49, 0xffff0000, v51
	v_and_b32_e32 v51, 0xffff0000, v53
	v_pk_fma_f32 v[36:37], v[36:37], v[50:51], v[48:49]
	v_cvt_pk_bf16_f32 v34, v34, v35
	v_cvt_pk_bf16_f32 v35, v36, v37
	global_store_dwordx2 v[62:63], v[34:35], off offset:288
	global_load_dwordx2 v[34:35], v[46:47], off offset:288
	s_nop 0
	global_load_dwordx2 v[36:37], v[66:67], off offset:288
	v_lshlrev_b32_e32 v48, 16, v68
	v_lshlrev_b32_e32 v50, 16, v70
	v_and_b32_e32 v49, 0xffff0000, v68
	v_and_b32_e32 v51, 0xffff0000, v70
	v_pk_fma_f32 v[30:31], v[30:31], v[50:51], v[48:49]
	v_lshlrev_b32_e32 v48, 16, v69
	v_lshlrev_b32_e32 v50, 16, v71
	v_and_b32_e32 v49, 0xffff0000, v69
	v_and_b32_e32 v51, 0xffff0000, v71
	v_pk_fma_f32 v[32:33], v[32:33], v[50:51], v[48:49]
	v_cvt_pk_bf16_f32 v30, v30, v31
	v_cvt_pk_bf16_f32 v31, v32, v33
	global_store_dwordx2 v[46:47], v[30:31], off
	v_lshlrev_b32_e32 v30, 16, v42
	v_lshlrev_b32_e32 v32, 16, v44
	v_and_b32_e32 v31, 0xffff0000, v42
	v_and_b32_e32 v33, 0xffff0000, v44
	v_pk_fma_f32 v[26:27], v[26:27], v[32:33], v[30:31]
	v_add_u32_e32 v30, 0xb0, v138
	v_ashrrev_i32_e32 v31, 31, v30
	v_lshlrev_b64 v[30:31], 11, v[30:31]
	v_lshl_add_u64 v[32:33], s[8:9], 0, v[30:31]
	v_lshl_add_u64 v[30:31], s[10:11], 0, v[30:31]
	v_lshl_add_u64 v[30:31], v[30:31], 0, v[140:141]
	v_lshl_add_u64 v[32:33], v[32:33], 0, v[140:141]
	global_load_dwordx2 v[48:49], v[30:31], off
	global_load_dwordx2 v[50:51], v[32:33], off
	v_lshlrev_b32_e32 v42, 16, v43
	v_lshlrev_b32_e32 v44, 16, v45
	v_and_b32_e32 v43, 0xffff0000, v43
	v_and_b32_e32 v45, 0xffff0000, v45
	v_pk_fma_f32 v[28:29], v[28:29], v[44:45], v[42:43]
	v_cvt_pk_bf16_f32 v26, v26, v27
	v_cvt_pk_bf16_f32 v27, v28, v29
	global_store_dwordx2 v[46:47], v[26:27], off offset:32
	global_load_dwordx2 v[42:43], v[30:31], off offset:32
	global_load_dwordx2 v[44:45], v[32:33], off offset:32
	s_waitcnt vmcnt(0)
; __device__ __forceinline__ float bflo(uint32_t v) { return __uint_as_float(v << 16); }
; __device__ __forceinline__ float bfhi(uint32_t v) { return __uint_as_float(v & 0xFFFF0000u); }
; template <class Epi, class Sched>
; __device__ __forceinline__ void gemm_phase(PG8_LAS unsigned char* lds, const Gemm g, const Sched& S, const Epi& E) {
;     ...
;         if (!has_next) break;
; #pragma unroll
;         for (int a = 0; a < 2; ++a)
; #pragma unroll
;             for (int b = 0; b < 2; ++b)
; #pragma unroll
;                 for (int m = 0; m < 4; ++m)
; #pragma unroll
;                     for (int n = 0; n < 2; ++n) acc[a][b][m][n] = (f32x4){0.f, 0.f, 0.f, 0.f};
;         cur = nxt; cA = nA; cB = nB; ++ui;
;     }
;   __device__ __forceinline__ void operator()(const acc8_t& acc, const pg8::Unit& u, int wr, int wc, int fr, int fq) const {
;     const u16* GB = (const u16*)(ws + OFF_GB); u16* M = (u16*)(ws + OFF_M);
; #pragma unroll
;     for (int ai = 0; ai < 2; ai++)
; #pragma unroll
;       for (int m = 0; m < 4; m++) {
;         const size_t token = EPI_TOKEN(u, ai, m);
; #pragma unroll
;         for (int bj = 0; bj < 2; bj++)
; #pragma unroll
;           for (int n = 0; n < 2; n++) {
;             const int f = EPI_COL(u, bj, n);
;             const uint2 gb = *(const uint2*)(GB + token * 1024 + f);
;             const uint2 mo = *(const uint2*)(M + token * 1024 + f);
;             uint2 o;
;             o.x = pack2(bflo(mo.x) + bflo(gb.x) * acc[ai][bj][m][n][0], bfhi(mo.x) + bfhi(gb.x) * acc[ai][bj][m][n][1]);
;             o.y = pack2(bflo(mo.y) + bflo(gb.y) * acc[ai][bj][m][n][2], bfhi(mo.y) + bfhi(gb.y) * acc[ai][bj][m][n][3]);
;             *(uint2*)(M + token * 1024 + f) = o;
;           }
;       }
;   }
	v_lshlrev_b32_e32 v26, 16, v38
	v_lshlrev_b32_e32 v28, 16, v40
	v_and_b32_e32 v27, 0xffff0000, v38
	v_and_b32_e32 v29, 0xffff0000, v40
	v_pk_fma_f32 v[22:23], v[22:23], v[28:29], v[26:27]
	v_lshlrev_b32_e32 v26, 16, v39
	v_lshlrev_b32_e32 v28, 16, v41
	v_and_b32_e32 v27, 0xffff0000, v39
	v_and_b32_e32 v29, 0xffff0000, v41
	v_pk_fma_f32 v[24:25], v[24:25], v[28:29], v[26:27]
	v_cvt_pk_bf16_f32 v22, v22, v23
	v_cvt_pk_bf16_f32 v23, v24, v25
	global_store_dwordx2 v[46:47], v[22:23], off offset:256
	v_lshlrev_b32_e32 v22, 16, v34
	v_lshlrev_b32_e32 v24, 16, v36
	v_and_b32_e32 v23, 0xffff0000, v34
	v_and_b32_e32 v25, 0xffff0000, v36
	global_load_dwordx2 v[26:27], v[30:31], off offset:256
	global_load_dwordx2 v[28:29], v[32:33], off offset:256
	v_pk_fma_f32 v[18:19], v[18:19], v[24:25], v[22:23]
	v_lshlrev_b32_e32 v22, 16, v35
	v_lshlrev_b32_e32 v24, 16, v37
	v_and_b32_e32 v23, 0xffff0000, v35
	v_and_b32_e32 v25, 0xffff0000, v37
	v_pk_fma_f32 v[20:21], v[20:21], v[24:25], v[22:23]
	v_cvt_pk_bf16_f32 v18, v18, v19
	v_cvt_pk_bf16_f32 v19, v20, v21
	global_store_dwordx2 v[46:47], v[18:19], off offset:288
	global_load_dwordx2 v[18:19], v[30:31], off offset:288
	s_nop 0
	global_load_dwordx2 v[20:21], v[32:33], off offset:288
	v_lshlrev_b32_e32 v22, 16, v48
	v_lshlrev_b32_e32 v24, 16, v50
	v_and_b32_e32 v23, 0xffff0000, v48
	v_and_b32_e32 v25, 0xffff0000, v50
	v_pk_fma_f32 v[14:15], v[14:15], v[24:25], v[22:23]
	v_lshlrev_b32_e32 v22, 16, v49
	v_lshlrev_b32_e32 v24, 16, v51
	v_and_b32_e32 v23, 0xffff0000, v49
	v_and_b32_e32 v25, 0xffff0000, v51
	v_pk_fma_f32 v[16:17], v[16:17], v[24:25], v[22:23]
	v_cvt_pk_bf16_f32 v14, v14, v15
	v_cvt_pk_bf16_f32 v15, v16, v17
	global_store_dwordx2 v[30:31], v[14:15], off
	v_lshlrev_b32_e32 v14, 16, v42
	v_lshlrev_b32_e32 v16, 16, v44
	v_and_b32_e32 v15, 0xffff0000, v42
	v_and_b32_e32 v17, 0xffff0000, v44
	v_pk_fma_f32 v[10:11], v[10:11], v[16:17], v[14:15]
	v_lshlrev_b32_e32 v14, 16, v43
	v_lshlrev_b32_e32 v16, 16, v45
	v_and_b32_e32 v15, 0xffff0000, v43
	v_and_b32_e32 v17, 0xffff0000, v45
	v_pk_fma_f32 v[12:13], v[12:13], v[16:17], v[14:15]
	v_cvt_pk_bf16_f32 v10, v10, v11
	v_cvt_pk_bf16_f32 v11, v12, v13
	global_store_dwordx2 v[30:31], v[10:11], off offset:32
	s_waitcnt vmcnt(0)
	v_lshlrev_b32_e32 v10, 16, v26
	v_lshlrev_b32_e32 v12, 16, v28
	v_and_b32_e32 v11, 0xffff0000, v26
	v_and_b32_e32 v13, 0xffff0000, v28
	v_pk_fma_f32 v[6:7], v[6:7], v[12:13], v[10:11]
	v_lshlrev_b32_e32 v10, 16, v27
	v_lshlrev_b32_e32 v12, 16, v29
	v_and_b32_e32 v11, 0xffff0000, v27
	v_and_b32_e32 v13, 0xffff0000, v29
	v_pk_fma_f32 v[8:9], v[8:9], v[12:13], v[10:11]
	v_cvt_pk_bf16_f32 v6, v6, v7
	v_cvt_pk_bf16_f32 v7, v8, v9
	global_store_dwordx2 v[30:31], v[6:7], off offset:256
	v_lshlrev_b32_e32 v6, 16, v18
	v_lshlrev_b32_e32 v8, 16, v20
	v_and_b32_e32 v7, 0xffff0000, v18
	v_and_b32_e32 v9, 0xffff0000, v20
	v_pk_fma_f32 v[2:3], v[2:3], v[8:9], v[6:7]
	v_lshlrev_b32_e32 v6, 16, v19
	v_lshlrev_b32_e32 v8, 16, v21
	v_and_b32_e32 v7, 0xffff0000, v19
	v_and_b32_e32 v9, 0xffff0000, v21
	v_pk_fma_f32 v[4:5], v[4:5], v[8:9], v[6:7]
	v_cvt_pk_bf16_f32 v2, v2, v3
	v_cvt_pk_bf16_f32 v3, v4, v5
	global_store_dwordx2 v[30:31], v[2:3], off offset:288
	s_cbranch_vccz .LBB0_707
	s_waitcnt vmcnt(0)
	s_cmpk_gt_u32 s33, 0xff
	s_cbranch_scc1 .LBB0_717
	s_barrier
